# v19 with non-temporal (nt) cache policy on the write-once final-output stores of the last stream-update phase
# baseline (speedup 1.0000x reference)
.Le0_p8:
	ds_bpermute_b32 v52, v56, v62
	v_lshlrev_b32_e32 v66, 16, v44
	v_and_b32_e32 v67, 0xffff0000, v44
	v_lshlrev_b32_e32 v64, 16, v36
	v_and_b32_e32 v65, 0xffff0000, v36
	s_waitcnt lgkmcnt(0)
	v_add_f32_e32 v52, v62, v52
	ds_bpermute_b32 v53, v57, v52
	v_lshlrev_b32_e32 v68, 16, v45
	v_and_b32_e32 v69, 0xffff0000, v45
	v_lshlrev_b32_e32 v70, 16, v46
	v_and_b32_e32 v71, 0xffff0000, v46
	s_waitcnt lgkmcnt(0)
	v_add_f32_e32 v52, v52, v53
	ds_bpermute_b32 v53, v58, v52
	v_lshlrev_b32_e32 v72, 16, v47
	v_and_b32_e32 v73, 0xffff0000, v47
	v_lshlrev_b32_e32 v74, 16, v40
	v_and_b32_e32 v75, 0xffff0000, v40
	s_waitcnt lgkmcnt(0)
	v_add_f32_e32 v52, v52, v53
	ds_bpermute_b32 v53, v59, v52
	v_lshlrev_b32_e32 v76, 16, v41
	v_and_b32_e32 v77, 0xffff0000, v41
	v_lshlrev_b32_e32 v78, 16, v42
	v_and_b32_e32 v79, 0xffff0000, v42
	s_waitcnt lgkmcnt(0)
	v_add_f32_e32 v52, v52, v53
	ds_bpermute_b32 v53, v60, v52
	v_lshlrev_b32_e32 v80, 16, v43
	v_and_b32_e32 v81, 0xffff0000, v43
	s_waitcnt lgkmcnt(0)
	v_add_f32_e32 v52, v52, v53
	ds_bpermute_b32 v53, v61, v52
	s_waitcnt lgkmcnt(0)
	v_add_f32_e32 v52, v52, v53
	v_fmamk_f32 v52, v52, 0x3a800000, v155
	v_cmp_gt_f32_e64 s[8:9], s69, v52
	v_mul_f32_e32 v53, 0x4b800000, v52
	s_nop 0
	v_cndmask_b32_e64 v52, v52, v53, s[8:9]
	v_rsq_f32_e32 v52, v52
	s_nop 0
	v_mul_f32_e32 v53, 0x45800000, v52
	v_cndmask_b32_e64 v52, v52, v53, s[8:9]
	v_pk_mul_f32 v[66:67], v[52:53], v[66:67] op_sel_hi:[0,1]
	v_pk_fma_f32 v[64:65], v[4:5], v[66:67], v[64:65]
	v_lshlrev_b32_e32 v66, 16, v37
	v_and_b32_e32 v67, 0xffff0000, v37
	v_pk_mul_f32 v[68:69], v[52:53], v[68:69] op_sel_hi:[0,1]
	v_pk_fma_f32 v[66:67], v[6:7], v[68:69], v[66:67]
	v_lshlrev_b32_e32 v68, 16, v38
	v_and_b32_e32 v69, 0xffff0000, v38
	v_pk_mul_f32 v[70:71], v[52:53], v[70:71] op_sel_hi:[0,1]
	v_pk_fma_f32 v[68:69], v[0:1], v[70:71], v[68:69]
	v_lshlrev_b32_e32 v70, 16, v39
	v_and_b32_e32 v71, 0xffff0000, v39
	v_pk_mul_f32 v[72:73], v[52:53], v[72:73] op_sel_hi:[0,1]
	v_pk_fma_f32 v[70:71], v[2:3], v[72:73], v[70:71]
	v_lshlrev_b32_e32 v72, 16, v32
	v_and_b32_e32 v73, 0xffff0000, v32
	v_pk_mul_f32 v[74:75], v[52:53], v[74:75] op_sel_hi:[0,1]
	v_pk_fma_f32 v[72:73], v[12:13], v[74:75], v[72:73]
	v_lshlrev_b32_e32 v74, 16, v33
	v_and_b32_e32 v75, 0xffff0000, v33
	v_pk_mul_f32 v[76:77], v[52:53], v[76:77] op_sel_hi:[0,1]
	v_pk_fma_f32 v[74:75], v[14:15], v[76:77], v[74:75]
	v_lshlrev_b32_e32 v76, 16, v34
	v_and_b32_e32 v77, 0xffff0000, v34
	v_pk_mul_f32 v[78:79], v[52:53], v[78:79] op_sel_hi:[0,1]
	v_pk_fma_f32 v[76:77], v[8:9], v[78:79], v[76:77]
	v_lshlrev_b32_e32 v78, 16, v35
	v_and_b32_e32 v79, 0xffff0000, v35
	v_pk_mul_f32 v[52:53], v[52:53], v[80:81] op_sel_hi:[0,1]
	v_pk_fma_f32 v[78:79], v[10:11], v[52:53], v[78:79]
	v_lshlrev_b64 v[52:53], 12, v[50:51]
	v_lshl_or_b32 v52, v54, 2, v52
	v_lshl_add_u64 v[52:53], s[86:87], 0, v[52:53]
	global_store_dwordx4 v[52:53], v[64:67], off nt
	global_store_dwordx4 v[52:53], v[68:71], off offset:16 nt
	global_store_dwordx4 v[52:53], v[72:75], off offset:2048 nt
	global_store_dwordx4 v[52:53], v[76:79], off offset:2064 nt

.Le0_p7:
	ds_bpermute_b32 v53, v56, v55
	v_lshlrev_b32_e32 v66, 16, v24
	v_and_b32_e32 v67, 0xffff0000, v24
	v_lshlrev_b32_e32 v64, 16, v16
	v_and_b32_e32 v65, 0xffff0000, v16
	s_waitcnt lgkmcnt(0)
	v_add_f32_e32 v53, v55, v53
	ds_bpermute_b32 v63, v57, v53
	v_lshlrev_b32_e32 v68, 16, v25
	v_and_b32_e32 v69, 0xffff0000, v25
	v_lshlrev_b32_e32 v70, 16, v26
	v_and_b32_e32 v71, 0xffff0000, v26
	s_waitcnt lgkmcnt(0)
	v_add_f32_e32 v53, v53, v63
	ds_bpermute_b32 v63, v58, v53
	v_lshlrev_b32_e32 v72, 16, v27
	v_and_b32_e32 v73, 0xffff0000, v27
	v_lshlrev_b32_e32 v74, 16, v28
	v_and_b32_e32 v75, 0xffff0000, v28
	s_waitcnt lgkmcnt(0)
	v_add_f32_e32 v53, v53, v63
	ds_bpermute_b32 v63, v59, v53
	v_lshlrev_b32_e32 v76, 16, v29
	v_and_b32_e32 v77, 0xffff0000, v29
	v_lshlrev_b32_e32 v80, 16, v30
	v_and_b32_e32 v81, 0xffff0000, v30
	s_waitcnt lgkmcnt(0)
	v_add_f32_e32 v53, v53, v63
	ds_bpermute_b32 v63, v60, v53
	v_lshlrev_b32_e32 v82, 16, v31
	v_and_b32_e32 v83, 0xffff0000, v31
	s_waitcnt lgkmcnt(0)
	v_add_f32_e32 v53, v53, v63
	ds_bpermute_b32 v63, v61, v53
	s_waitcnt lgkmcnt(0)
	v_add_f32_e32 v53, v53, v63
	v_fmamk_f32 v53, v53, 0x3a800000, v155
	v_cmp_gt_f32_e64 s[10:11], s69, v53
	v_mul_f32_e32 v63, 0x4b800000, v53
	s_nop 0
	v_cndmask_b32_e64 v53, v53, v63, s[10:11]
	v_rsq_f32_e32 v53, v53
	s_nop 0
	v_mul_f32_e32 v63, 0x45800000, v53
	v_cndmask_b32_e64 v78, v53, v63, s[10:11]
	v_pk_mul_f32 v[66:67], v[78:79], v[66:67] op_sel_hi:[0,1]
	v_pk_fma_f32 v[64:65], v[4:5], v[66:67], v[64:65]
	v_lshlrev_b32_e32 v66, 16, v17
	v_and_b32_e32 v67, 0xffff0000, v17
	v_pk_mul_f32 v[68:69], v[78:79], v[68:69] op_sel_hi:[0,1]
	v_pk_fma_f32 v[66:67], v[6:7], v[68:69], v[66:67]
	v_lshlrev_b32_e32 v68, 16, v18
	v_and_b32_e32 v69, 0xffff0000, v18
	v_pk_mul_f32 v[70:71], v[78:79], v[70:71] op_sel_hi:[0,1]
	v_pk_fma_f32 v[68:69], v[0:1], v[70:71], v[68:69]
	v_lshlrev_b32_e32 v70, 16, v19
	v_and_b32_e32 v71, 0xffff0000, v19
	v_pk_mul_f32 v[72:73], v[78:79], v[72:73] op_sel_hi:[0,1]
	v_pk_fma_f32 v[70:71], v[2:3], v[72:73], v[70:71]
	v_lshlrev_b32_e32 v72, 16, v20
	v_and_b32_e32 v73, 0xffff0000, v20
	v_pk_mul_f32 v[74:75], v[78:79], v[74:75] op_sel_hi:[0,1]
	v_pk_fma_f32 v[72:73], v[12:13], v[74:75], v[72:73]
	v_lshlrev_b32_e32 v74, 16, v21
	v_and_b32_e32 v75, 0xffff0000, v21
	v_pk_mul_f32 v[76:77], v[78:79], v[76:77] op_sel_hi:[0,1]
	v_pk_fma_f32 v[74:75], v[14:15], v[76:77], v[74:75]
	v_lshlrev_b32_e32 v76, 16, v22
	v_and_b32_e32 v77, 0xffff0000, v22
	v_pk_mul_f32 v[80:81], v[78:79], v[80:81] op_sel_hi:[0,1]
	v_pk_fma_f32 v[76:77], v[8:9], v[80:81], v[76:77]
	v_lshlrev_b32_e32 v80, 16, v23
	v_and_b32_e32 v81, 0xffff0000, v23
	v_pk_mul_f32 v[78:79], v[78:79], v[82:83] op_sel_hi:[0,1]
	v_ashrrev_i32_e32 v53, 31, v52
	v_pk_fma_f32 v[78:79], v[10:11], v[78:79], v[80:81]
	v_lshlrev_b64 v[80:81], 12, v[52:53]
	v_lshl_or_b32 v80, v54, 2, v80
	v_lshl_add_u64 v[80:81], s[86:87], 0, v[80:81]
	global_store_dwordx4 v[80:81], v[64:67], off nt
	global_store_dwordx4 v[80:81], v[68:71], off offset:16 nt
	global_store_dwordx4 v[80:81], v[72:75], off offset:2048 nt
	global_store_dwordx4 v[80:81], v[76:79], off offset:2064 nt
	s_and_saveexec_b64 s[10:11], s[8:9]
	s_cbranch_execz .LBB0_1165
	v_add_u32_e32 v52, s19, v52
	v_cmp_gt_i32_e64 s[8:9], s33, v52
	s_and_saveexec_b64 s[6:7], s[8:9]
	s_cbranch_execz .LBB0_1164
	v_ashrrev_i32_e32 v53, 31, v52
	v_lshlrev_b64 v[24:25], 11, v[52:53]
	v_lshl_or_b32 v24, v54, 1, v24
	v_lshl_add_u64 v[20:21], s[56:57], 0, v[24:25]
	v_lshl_add_u64 v[28:29], s[20:21], 0, v[24:25]
	global_load_dwordx4 v[16:19], v[20:21], off
	s_nop 0
	global_load_dwordx4 v[20:23], v[20:21], off offset:1024
	s_nop 0
	global_load_dwordx4 v[24:27], v[28:29], off
	s_nop 0
	global_load_dwordx4 v[28:31], v[28:29], off offset:1024
	v_mov_b32_e32 v55, 0
	s_and_saveexec_b64 s[8:9], vcc
	s_cbranch_execz .LBB0_1163
	v_lshlrev_b64 v[52:53], 6, v[52:53]
	v_lshl_add_u64 v[52:53], v[48:49], 0, v[52:53]
	global_load_dword v55, v[52:53], off
	s_or_b64 exec, exec, s[8:9]
	s_or_b64 exec, exec, s[6:7]
	s_waitcnt vmcnt(5)
	s_branch .Le0_p8
